# conv_and_window conv loop rewritten by hand: per-wave row pair, all loads up front + next-iteration prefetch, scalar control flow
# speedup vs baseline: 1.0254x; 1.0082x over previous
; DEV int tidx() { int t = threadIdx.x; asm volatile("" : "+v"(t)); return t; }
; DEV int bidx() { int t = blockIdx.x; asm volatile("" : "+s"(t)); return t; }
; DEV float bflo(unsigned w) { return __uint_as_float(w << 16); }
; DEV float bfhi(unsigned w) { return __uint_as_float(w & 0xffff0000u); }
; DEV void conv_and_window(const Params& p, int l) {
;     ...
;   const int gtid = bidx() * 512 + tidx(), gstride = gridDim.x * 512;
;   const float* cw = p.in[I_CONVW] + l * 3 * 512;
;   for (int c = gtid; c < (MTOK / 2) * 64; c += gstride) {
;     const int row = (c >> 6) * 2, c8 = (c & 63) * 8;
;     int t, b; const bool samp = row >= TP;
;     if (!samp) { t = row & (SEQ - 1); b = row >> 12; } else { t = (row - TP) & 7; b = (row - TP) >> 3; }
;     const int T = samp ? 8 : SEQ;
;     float u[4][8];
; #pragma unroll
;     for (int k = 0; k < 4; ++k) {
;       if (k >= 2 || t >= 2) {
;         const size_t ro = (size_t)(row - 2 + k) * NIN;
;         const u32x4 a = *(const u32x4*)(Z + ro + CC + c8), hq = *(const u32x4*)(Z + ro + CH + c8);
;         u[k][0] = bflo(a.x) * bflo(hq.x); u[k][1] = bfhi(a.x) * bfhi(hq.x); u[k][2] = bflo(a.y) * bflo(hq.y); u[k][3] = bfhi(a.y) * bfhi(hq.y);
;         u[k][4] = bflo(a.z) * bflo(hq.z); u[k][5] = bfhi(a.z) * bfhi(hq.z); u[k][6] = bflo(a.w) * bflo(hq.w); u[k][7] = bfhi(a.w) * bfhi(hq.w);
;       } else {
; #pragma unroll
;         for (int i = 0; i < 8; ++i) u[k][i] = samp ? p.in[I_SCONV][(size_t)((l * 128 + b) * 2 + k) * 512 + c8 + i] : 0.f;
;       }
;     }
;     float w0[8], w1[8], w2[8];
; #pragma unroll
;     for (int i = 0; i < 8; ++i) { w0[i] = cw[c8 + i]; w1[i] = cw[512 + c8 + i]; w2[i] = cw[1024 + c8 + i]; }
.LBB0_364:
	v_readlane_b32 s2, v250, 16
	s_mov_b32 s0, s74
	v_mov_b32_e32 v45, v171
	v_readlane_b32 s3, v250, 17
	s_load_dword s1, s[2:3], 0x10
	s_load_dword s4, s[2:3], 0x0
	v_lshl_add_u32 v44, s0, 9, v45
	v_cmp_gt_i32_e32 vcc, s35, v44
	s_waitcnt lgkmcnt(0)
	s_lshr_b32 s1, s1, 16
	s_cmp_lg_u32 s1, 0
	s_cselect_b64 s[2:3], -1, 0
	s_cmp_lg_u64 s[2:3], 0
	s_addc_u32 s16, s4, 0
	s_lshl_b32 s6, s16, 9
	s_and_saveexec_b64 s[2:3], vcc
	s_mov_b32 s26, 0x3450000
	s_cbranch_execz .LBB0_413
	v_readlane_b32 s4, v248, 43
	v_readlane_b32 s5, v248, 44
	s_mov_b32 s8, s4
	s_mulk_i32 s4, 0x600
	s_ashr_i32 s5, s4, 31
	s_lshl_b64 s[4:5], s[4:5], 2
	s_add_u32 s4, s80, s4
	v_lshlrev_b32_e32 v0, 3, v45
	s_addc_u32 s5, s81, s5
	s_lshl_b32 s17, s8, 8
	s_lshl_b32 s18, s8, 3
	v_lshl_add_u32 v64, s0, 12, v0
	s_lshl_b32 s19, s16, 12
	s_mov_b64 s[8:9], 0
	v_mov_b32_e32 v65, v44
	v_readfirstlane_b32 s8, v44
	v_lshlrev_b32_e32 v160, 4, v202
	v_lshlrev_b32_e32 v161, 5, v202
	v_readlane_b32 s58, v248, 34
	v_readlane_b32 s59, v248, 35
	s_lshr_b32 s8, s8, 6
	s_add_u32 s56, s4, 0x1000
	s_addc_u32 s57, s5, 0
	global_load_dwordx4 v[0:3], v161, s[4:5] offset:0
	global_load_dwordx4 v[4:7], v161, s[4:5] offset:16
	global_load_dwordx4 v[8:11], v161, s[4:5] offset:2048
	global_load_dwordx4 v[12:15], v161, s[4:5] offset:2064
	global_load_dwordx4 v[16:19], v161, s[56:57]
	global_load_dwordx4 v[20:23], v161, s[56:57] offset:16
	s_lshl_b32 s9, s8, 1
	s_mul_i32 s0, s9, 0x3600
	s_add_u32 s48, s30, s0
	s_addc_u32 s49, s31, 0
	s_add_u32 s48, s48, 0x1600
	s_addc_u32 s49, s49, 0
	s_sub_u32 s46, s48, 0x3600
	s_subb_u32 s47, s49, 0
	s_sub_u32 s44, s46, 0x3600
	s_subb_u32 s45, s47, 0
	s_add_u32 s50, s48, 0x3600
	s_addc_u32 s51, s49, 0
	global_load_dwordx4 v[68:71], v160, s[44:45]
	global_load_dwordx4 v[72:75], v160, s[44:45] offset:1024
	global_load_dwordx4 v[76:79], v160, s[46:47]
	global_load_dwordx4 v[80:83], v160, s[46:47] offset:1024
	global_load_dwordx4 v[84:87], v160, s[48:49]
	global_load_dwordx4 v[88:91], v160, s[48:49] offset:1024
	global_load_dwordx4 v[92:95], v160, s[50:51]
	global_load_dwordx4 v[96:99], v160, s[50:51] offset:1024
	global_load_dwordx4 v[100:103], v160, s[48:49] offset:-1024
	global_load_dwordx4 v[104:107], v160, s[50:51] offset:-1024
	s_waitcnt vmcnt(0)
.Lconv_loop:
	v_lshlrev_b32_e32 v108, 16, v68
	v_and_b32_e32 v109, 0xffff0000, v68
	v_lshlrev_b32_e32 v148, 16, v72
	v_and_b32_e32 v149, 0xffff0000, v72
	v_mul_f32_e32 v108, v108, v148
	v_mul_f32_e32 v109, v109, v149
	v_lshlrev_b32_e32 v110, 16, v69
	v_and_b32_e32 v111, 0xffff0000, v69
	v_lshlrev_b32_e32 v148, 16, v73
	v_and_b32_e32 v149, 0xffff0000, v73
	v_mul_f32_e32 v110, v110, v148
	v_mul_f32_e32 v111, v111, v149
	v_lshlrev_b32_e32 v112, 16, v70
	v_and_b32_e32 v113, 0xffff0000, v70
	v_lshlrev_b32_e32 v148, 16, v74
	v_and_b32_e32 v149, 0xffff0000, v74
	v_mul_f32_e32 v112, v112, v148
	v_mul_f32_e32 v113, v113, v149
	v_lshlrev_b32_e32 v114, 16, v71
	v_and_b32_e32 v115, 0xffff0000, v71
	v_lshlrev_b32_e32 v148, 16, v75
	v_and_b32_e32 v149, 0xffff0000, v75
	v_mul_f32_e32 v114, v114, v148
	v_mul_f32_e32 v115, v115, v149
	v_lshlrev_b32_e32 v116, 16, v76
	v_and_b32_e32 v117, 0xffff0000, v76
	v_lshlrev_b32_e32 v148, 16, v80
	v_and_b32_e32 v149, 0xffff0000, v80
	v_mul_f32_e32 v116, v116, v148
	v_mul_f32_e32 v117, v117, v149
	v_lshlrev_b32_e32 v118, 16, v77
	v_and_b32_e32 v119, 0xffff0000, v77
	v_lshlrev_b32_e32 v148, 16, v81
	v_and_b32_e32 v149, 0xffff0000, v81
	v_mul_f32_e32 v118, v118, v148
	v_mul_f32_e32 v119, v119, v149
	v_lshlrev_b32_e32 v120, 16, v78
	v_and_b32_e32 v121, 0xffff0000, v78
	v_lshlrev_b32_e32 v148, 16, v82
	v_and_b32_e32 v149, 0xffff0000, v82
	v_mul_f32_e32 v120, v120, v148
	v_mul_f32_e32 v121, v121, v149
	v_lshlrev_b32_e32 v122, 16, v79
	v_and_b32_e32 v123, 0xffff0000, v79
	v_lshlrev_b32_e32 v148, 16, v83
	v_and_b32_e32 v149, 0xffff0000, v83
	v_mul_f32_e32 v122, v122, v148
	v_mul_f32_e32 v123, v123, v149
	v_lshlrev_b32_e32 v124, 16, v84
	v_and_b32_e32 v125, 0xffff0000, v84
	v_lshlrev_b32_e32 v148, 16, v88
	v_and_b32_e32 v149, 0xffff0000, v88
	v_mul_f32_e32 v124, v124, v148
	v_mul_f32_e32 v125, v125, v149
	v_lshlrev_b32_e32 v126, 16, v85
	v_and_b32_e32 v127, 0xffff0000, v85
	v_lshlrev_b32_e32 v148, 16, v89
	v_and_b32_e32 v149, 0xffff0000, v89
	v_mul_f32_e32 v126, v126, v148
	v_mul_f32_e32 v127, v127, v149
	v_lshlrev_b32_e32 v128, 16, v86
	v_and_b32_e32 v129, 0xffff0000, v86
	v_lshlrev_b32_e32 v148, 16, v90
	v_and_b32_e32 v149, 0xffff0000, v90
	v_mul_f32_e32 v128, v128, v148
	v_mul_f32_e32 v129, v129, v149
	v_lshlrev_b32_e32 v130, 16, v87
	v_and_b32_e32 v131, 0xffff0000, v87
	v_lshlrev_b32_e32 v148, 16, v91
	v_and_b32_e32 v149, 0xffff0000, v91
	v_mul_f32_e32 v130, v130, v148
	v_mul_f32_e32 v131, v131, v149
	v_lshlrev_b32_e32 v132, 16, v92
	v_and_b32_e32 v133, 0xffff0000, v92
	v_lshlrev_b32_e32 v148, 16, v96
	v_and_b32_e32 v149, 0xffff0000, v96
	v_mul_f32_e32 v132, v132, v148
	v_mul_f32_e32 v133, v133, v149
	v_lshlrev_b32_e32 v134, 16, v93
	v_and_b32_e32 v135, 0xffff0000, v93
	v_lshlrev_b32_e32 v148, 16, v97
	v_and_b32_e32 v149, 0xffff0000, v97
	v_mul_f32_e32 v134, v134, v148
	v_mul_f32_e32 v135, v135, v149
	v_lshlrev_b32_e32 v136, 16, v94
	v_and_b32_e32 v137, 0xffff0000, v94
	v_lshlrev_b32_e32 v148, 16, v98
	v_and_b32_e32 v149, 0xffff0000, v98
	v_mul_f32_e32 v136, v136, v148
	v_mul_f32_e32 v137, v137, v149
	v_lshlrev_b32_e32 v138, 16, v95
	v_and_b32_e32 v139, 0xffff0000, v95
	v_lshlrev_b32_e32 v148, 16, v99
	v_and_b32_e32 v149, 0xffff0000, v99
	v_mul_f32_e32 v138, v138, v148
	v_mul_f32_e32 v139, v139, v149
	v_mov_b64_e32 v[140:141], v[100:101]
	v_mov_b64_e32 v[142:143], v[102:103]
	v_mov_b64_e32 v[144:145], v[104:105]
	v_mov_b64_e32 v[146:147], v[106:107]
	s_mov_b64 s[52:53], s[48:49]
	s_mov_b64 s[54:55], s[50:51]
	s_cmp_ge_u32 s9, 0x4000
	s_cselect_b32 s38, 1, 0
	s_sub_u32 s0, s9, 0x4000
	s_and_b32 s1, s0, 7
	s_lshr_b32 s0, s0, 3
	s_and_b32 s12, s9, 0xfff
	s_lshr_b32 s13, s9, 12
	s_cmp_eq_u32 s38, 1
	s_cselect_b32 s39, s1, s12
	s_cselect_b32 s12, s0, s13
	s_cselect_b32 s13, 6, 0xffe
	s_cmp_lg_u32 s39, 0
	s_cbranch_scc1 .Lconv_nofirst
	s_cmp_eq_u32 s38, 1
	s_cbranch_scc1 .Lconv_state
	v_mov_b64_e32 v[108:109], 0
	v_mov_b64_e32 v[110:111], 0
	v_mov_b64_e32 v[112:113], 0
	v_mov_b64_e32 v[114:115], 0
	v_mov_b64_e32 v[116:117], 0
	v_mov_b64_e32 v[118:119], 0
	v_mov_b64_e32 v[120:121], 0
	v_mov_b64_e32 v[122:123], 0
	s_branch .Lconv_nofirst
; DEV unsigned cvt_pk_bf16(float lo, float hi) { const f32x2_ v = {lo, hi}; return __builtin_bit_cast(unsigned, __builtin_convertvector(v, bf16x2n_)); }
; DEV float bflo(unsigned w) { return __uint_as_float(w << 16); }
; DEV float bfhi(unsigned w) { return __uint_as_float(w & 0xffff0000u); }
; DEV void conv_and_window(const Params& p, int l) {
;     ...
;       if (k >= 2 || t >= 2) {
;         const size_t ro = (size_t)(row - 2 + k) * NIN;
;         const u32x4 a = *(const u32x4*)(Z + ro + CC + c8), hq = *(const u32x4*)(Z + ro + CH + c8);
;         u[k][0] = bflo(a.x) * bflo(hq.x); u[k][1] = bfhi(a.x) * bfhi(hq.x); u[k][2] = bflo(a.y) * bflo(hq.y); u[k][3] = bfhi(a.y) * bfhi(hq.y);
;         u[k][4] = bflo(a.z) * bflo(hq.z); u[k][5] = bfhi(a.z) * bfhi(hq.z); u[k][6] = bflo(a.w) * bflo(hq.w); u[k][7] = bfhi(a.w) * bfhi(hq.w);
;       } else {
; #pragma unroll
;         for (int i = 0; i < 8; ++i) u[k][i] = samp ? p.in[I_SCONV][(size_t)((l * 128 + b) * 2 + k) * 512 + c8 + i] : 0.f;
;       }
;     }
;     float w0[8], w1[8], w2[8];
; #pragma unroll
;     for (int i = 0; i < 8; ++i) { w0[i] = cw[c8 + i]; w1[i] = cw[512 + c8 + i]; w2[i] = cw[1024 + c8 + i]; }
; #pragma unroll
;     for (int k = 0; k < 2; ++k) {
;       const size_t ro = (size_t)(row + k) * NIN;
;       const u32x4 cbv = *(const u32x4*)(Zw + ro + CB + c8);
;       const float cbf[8] = {bflo(cbv.x), bfhi(cbv.x), bflo(cbv.y), bfhi(cbv.y), bflo(cbv.z), bfhi(cbv.z), bflo(cbv.w), bfhi(cbv.w)};
;       float o[8];
; #pragma unroll
;       for (int i = 0; i < 8; ++i) o[i] = cbf[i] * (w0[i] * u[k][i] + w1[i] * u[k + 1][i] + w2[i] * u[k + 2][i]);
;       u32x4 ow; ow.x = cvt_pk_bf16(o[0], o[1]); ow.y = cvt_pk_bf16(o[2], o[3]); ow.z = cvt_pk_bf16(o[4], o[5]); ow.w = cvt_pk_bf16(o[6], o[7]);
;       *(u32x4*)(Zw + ro + CB + c8) = ow;
;     }
;     if (t == T - 2) {
; #pragma unroll
;       for (int k = 0; k < 2; ++k) {
;         float* dst = samp ? p.out + O_CONVS + (size_t)((l * 128 + b) * 2 + k) * 512 + c8
;                           : p.out + O_CONVP + (size_t)((l * 4 + b) * 2 + k) * 512 + c8;
; #pragma unroll
;         for (int i = 0; i < 8; ++i) dst[i] = u[2 + k][i];
;       }
;     }
;   }
.Lconv_state:
	s_lshl_b32 s0, s17, 11
	s_lshl_b32 s1, s12, 12
	s_add_u32 s0, s0, s1
	s_add_u32 s56, s58, s0
	s_addc_u32 s57, s59, 0
	global_load_dwordx4 v[108:111], v161, s[56:57] offset:0
	global_load_dwordx4 v[112:115], v161, s[56:57] offset:16
	global_load_dwordx4 v[116:119], v161, s[56:57] offset:2048
	global_load_dwordx4 v[120:123], v161, s[56:57] offset:2064
	s_waitcnt vmcnt(0)
.Lconv_nofirst:
	s_add_u32 s8, s8, 0x800
	s_cmp_lt_u32 s8, 0x2200
	s_cselect_b32 s14, 1, 0
	s_mov_b32 s15, s9
	s_cbranch_scc0 .Lconv_noload
	s_lshl_b32 s9, s8, 1
	s_mul_i32 s0, s9, 0x3600
	s_add_u32 s48, s30, s0
	s_addc_u32 s49, s31, 0
	s_add_u32 s48, s48, 0x1600
	s_addc_u32 s49, s49, 0
	s_sub_u32 s46, s48, 0x3600
	s_subb_u32 s47, s49, 0
	s_sub_u32 s44, s46, 0x3600
	s_subb_u32 s45, s47, 0
	s_add_u32 s50, s48, 0x3600
	s_addc_u32 s51, s49, 0
	global_load_dwordx4 v[68:71], v160, s[44:45]
	global_load_dwordx4 v[72:75], v160, s[44:45] offset:1024
	global_load_dwordx4 v[76:79], v160, s[46:47]
	global_load_dwordx4 v[80:83], v160, s[46:47] offset:1024
	global_load_dwordx4 v[84:87], v160, s[48:49]
	global_load_dwordx4 v[88:91], v160, s[48:49] offset:1024
	global_load_dwordx4 v[92:95], v160, s[50:51]
	global_load_dwordx4 v[96:99], v160, s[50:51] offset:1024
	global_load_dwordx4 v[100:103], v160, s[48:49] offset:-1024
	global_load_dwordx4 v[104:107], v160, s[50:51] offset:-1024
.Lconv_noload:
	v_mul_f32_e32 v150, v0, v108
	v_fmac_f32_e32 v150, v8, v116
	v_fmac_f32_e32 v150, v16, v124
	v_mul_f32_e32 v151, v1, v109
	v_fmac_f32_e32 v151, v9, v117
	v_fmac_f32_e32 v151, v17, v125
	v_lshlrev_b32_e32 v148, 16, v140
	v_and_b32_e32 v149, 0xffff0000, v140
	v_mul_f32_e32 v150, v148, v150
	v_mul_f32_e32 v151, v149, v151
	v_cvt_pk_bf16_f32 v156, v150, v151
	v_mul_f32_e32 v150, v2, v110
	v_fmac_f32_e32 v150, v10, v118
	v_fmac_f32_e32 v150, v18, v126
	v_mul_f32_e32 v151, v3, v111
	v_fmac_f32_e32 v151, v11, v119
	v_fmac_f32_e32 v151, v19, v127
	v_lshlrev_b32_e32 v148, 16, v141
	v_and_b32_e32 v149, 0xffff0000, v141
	v_mul_f32_e32 v150, v148, v150
	v_mul_f32_e32 v151, v149, v151
	v_cvt_pk_bf16_f32 v157, v150, v151
	v_mul_f32_e32 v150, v4, v112
	v_fmac_f32_e32 v150, v12, v120
	v_fmac_f32_e32 v150, v20, v128
	v_mul_f32_e32 v151, v5, v113
	v_fmac_f32_e32 v151, v13, v121
	v_fmac_f32_e32 v151, v21, v129
	v_lshlrev_b32_e32 v148, 16, v142
	v_and_b32_e32 v149, 0xffff0000, v142
	v_mul_f32_e32 v150, v148, v150
	v_mul_f32_e32 v151, v149, v151
	v_cvt_pk_bf16_f32 v158, v150, v151
	v_mul_f32_e32 v150, v6, v114
	v_fmac_f32_e32 v150, v14, v122
	v_fmac_f32_e32 v150, v22, v130
	v_mul_f32_e32 v151, v7, v115
	v_fmac_f32_e32 v151, v15, v123
	v_fmac_f32_e32 v151, v23, v131
	v_lshlrev_b32_e32 v148, 16, v143
	v_and_b32_e32 v149, 0xffff0000, v143
	v_mul_f32_e32 v150, v148, v150
	v_mul_f32_e32 v151, v149, v151
	v_cvt_pk_bf16_f32 v159, v150, v151
	global_store_dwordx4 v160, v[156:159], s[52:53] offset:-1024
	s_nop 1
	v_mul_f32_e32 v150, v0, v116
	v_fmac_f32_e32 v150, v8, v124
	v_fmac_f32_e32 v150, v16, v132
	v_mul_f32_e32 v151, v1, v117
	v_fmac_f32_e32 v151, v9, v125
	v_fmac_f32_e32 v151, v17, v133
	v_lshlrev_b32_e32 v148, 16, v144
	v_and_b32_e32 v149, 0xffff0000, v144
	v_mul_f32_e32 v150, v148, v150
	v_mul_f32_e32 v151, v149, v151
	v_cvt_pk_bf16_f32 v156, v150, v151
	v_mul_f32_e32 v150, v2, v118
	v_fmac_f32_e32 v150, v10, v126
	v_fmac_f32_e32 v150, v18, v134
	v_mul_f32_e32 v151, v3, v119
	v_fmac_f32_e32 v151, v11, v127
	v_fmac_f32_e32 v151, v19, v135
	v_lshlrev_b32_e32 v148, 16, v145
	v_and_b32_e32 v149, 0xffff0000, v145
	v_mul_f32_e32 v150, v148, v150
	v_mul_f32_e32 v151, v149, v151
	v_cvt_pk_bf16_f32 v157, v150, v151
	v_mul_f32_e32 v150, v4, v120
	v_fmac_f32_e32 v150, v12, v128
	v_fmac_f32_e32 v150, v20, v136
	v_mul_f32_e32 v151, v5, v121
	v_fmac_f32_e32 v151, v13, v129
	v_fmac_f32_e32 v151, v21, v137
	v_lshlrev_b32_e32 v148, 16, v146
	v_and_b32_e32 v149, 0xffff0000, v146
	v_mul_f32_e32 v150, v148, v150
	v_mul_f32_e32 v151, v149, v151
	v_cvt_pk_bf16_f32 v158, v150, v151
	v_mul_f32_e32 v150, v6, v122
	v_fmac_f32_e32 v150, v14, v130
	v_fmac_f32_e32 v150, v22, v138
	v_mul_f32_e32 v151, v7, v123
	v_fmac_f32_e32 v151, v15, v131
	v_fmac_f32_e32 v151, v23, v139
	v_lshlrev_b32_e32 v148, 16, v147
	v_and_b32_e32 v149, 0xffff0000, v147
	v_mul_f32_e32 v150, v148, v150
	v_mul_f32_e32 v151, v149, v151
	v_cvt_pk_bf16_f32 v159, v150, v151
	global_store_dwordx4 v160, v[156:159], s[54:55] offset:-1024
	s_cmp_lg_u32 s39, s13
	s_cbranch_scc1 .Lconv_nolast
	s_cmp_eq_u32 s38, 1
	s_cselect_b32 s0, s17, s18
	s_mov_b32 s1, 0x4600000
	s_mov_b32 s56, 0x8608000
	s_cselect_b32 s1, s56, s1
	s_lshl_b32 s0, s0, 11
	s_lshl_b32 s56, s12, 12
	s_add_u32 s0, s0, s56
	s_add_u32 s0, s0, s1
	s_add_u32 s56, s22, s0
	s_addc_u32 s57, s23, 0
	global_store_dwordx4 v161, v[124:127], s[56:57] offset:0
	global_store_dwordx4 v161, v[128:131], s[56:57] offset:16
	global_store_dwordx4 v161, v[132:135], s[56:57] offset:2048
	global_store_dwordx4 v161, v[136:139], s[56:57] offset:2064
.Lconv_nolast:
	s_cmp_eq_u32 s14, 0
	s_cbranch_scc1 .LBB0_413
	s_waitcnt vmcnt(2)
	s_branch .Lconv_loop
